# hand-scheduled w_in epilogues in both layers (gelu chains interleaved 8-way, folded gelu constants, scalar FMAs, v_rsq); SwiGLU epilogues hand-scheduled; pipelined norm1 loop; weight-set-2 transposes
# speedup vs baseline: 1.0251x; 1.0016x over previous
.LBB0_200:
	v_lshl_or_b32 v226, s10, 8, v183
	v_lshl_add_u32 v222, v1, 2, s11
	ds_read_b32 v214, v222
	ds_read_b32 v215, v222 offset:64
	ds_read_b32 v216, v222 offset:128
	ds_read_b32 v217, v222 offset:192
	ds_read_b32 v218, v222 offset:512
	ds_read_b32 v219, v222 offset:576
	ds_read_b32 v220, v222 offset:640
	ds_read_b32 v221, v222 offset:704
	s_lshl_b32 s3, s96, 2
	s_add_i32 s3, s11, s3
	v_lshl_add_u32 v223, v174, 2, s3
	s_lshl_b32 s23, s14, 8
	ds_read_b128 v[42:45], v223 offset:1024
	ds_read_b128 v[46:49], v223 offset:1040
	ds_read_b128 v[38:41], v223 offset:1536
	ds_read_b128 v[34:37], v223 offset:1552
	v_ashrrev_i32_e32 v227, 31, v226
	v_lshlrev_b64 v[226:227], 1, v[226:227]
	v_lshl_add_u64 v[226:227], s[44:45], 0, v[226:227]
	v_xor_b32_e32 v224, 16, v189
	v_xor_b32_e32 v225, 32, v189
	v_lshlrev_b32_e32 v224, 2, v224
	v_lshlrev_b32_e32 v225, 2, v225
	v_mov_b32_e32 v170, 0xbdd2d3e7
	s_waitcnt lgkmcnt(4)
	v_fmamk_f32 v214, v214, 0x3a800000, v187
	v_fmamk_f32 v215, v215, 0x3a800000, v187
	v_fmamk_f32 v216, v216, 0x3a800000, v187
	v_fmamk_f32 v217, v217, 0x3a800000, v187
	v_fmamk_f32 v218, v218, 0x3a800000, v187
	v_fmamk_f32 v219, v219, 0x3a800000, v187
	v_fmamk_f32 v220, v220, 0x3a800000, v187
	v_fmamk_f32 v221, v221, 0x3a800000, v187
	v_rsq_f32_e32 v214, v214
	v_rsq_f32_e32 v215, v215
	v_rsq_f32_e32 v216, v216
	v_rsq_f32_e32 v217, v217
	v_rsq_f32_e32 v218, v218
	v_rsq_f32_e32 v219, v219
	v_rsq_f32_e32 v220, v220
	v_rsq_f32_e32 v221, v221
	s_waitcnt lgkmcnt(0)
	s_add_i32 s3, s10, -3
	s_cmp_gt_u32 s3, 1
	s_cbranch_scc1 .Lwin_plain_l0
	v_fma_f32 v142, v142, v214, v42
	v_fma_f32 v143, v143, v214, v43
	v_fma_f32 v144, v144, v214, v44
	v_fma_f32 v145, v145, v214, v45
	v_fma_f32 v138, v138, v214, v46
	v_fma_f32 v139, v139, v214, v47
	v_fma_f32 v140, v140, v214, v48
	v_fma_f32 v141, v141, v214, v49
	v_mul_f32_e32 v190, v142, v142
	v_mul_f32_e32 v191, v143, v143
	v_mul_f32_e32 v192, v144, v144
	v_mul_f32_e32 v193, v145, v145
	v_mul_f32_e32 v194, v138, v138
	v_mul_f32_e32 v195, v139, v139
	v_mul_f32_e32 v196, v140, v140
	v_mul_f32_e32 v197, v141, v141
	v_fmaak_f32 v190, v190, v170, 0xc0135761
	v_fmaak_f32 v191, v191, v170, 0xc0135761
	v_fmaak_f32 v192, v192, v170, 0xc0135761
	v_fmaak_f32 v193, v193, v170, 0xc0135761
	v_fmaak_f32 v194, v194, v170, 0xc0135761
	v_fmaak_f32 v195, v195, v170, 0xc0135761
	v_fmaak_f32 v196, v196, v170, 0xc0135761
	v_fmaak_f32 v197, v197, v170, 0xc0135761
	v_add_u32_e32 v169, s23, v1
	v_mad_i64_i32 v[228:229], s[8:9], v169, s22, v[226:227]
	v_mul_f32_e32 v190, v190, v142
	v_mul_f32_e32 v191, v191, v143
	v_mul_f32_e32 v192, v192, v144
	v_mul_f32_e32 v193, v193, v145
	v_mul_f32_e32 v194, v194, v138
	v_mul_f32_e32 v195, v195, v139
	v_mul_f32_e32 v196, v196, v140
	v_mul_f32_e32 v197, v197, v141
	v_exp_f32_e32 v190, v190
	v_exp_f32_e32 v191, v191
	v_exp_f32_e32 v192, v192
	v_exp_f32_e32 v193, v193
	v_exp_f32_e32 v194, v194
	v_exp_f32_e32 v195, v195
	v_exp_f32_e32 v196, v196
	v_exp_f32_e32 v197, v197
	v_add_f32_e32 v190, 1.0, v190
	v_add_f32_e32 v191, 1.0, v191
	v_add_f32_e32 v192, 1.0, v192
	v_add_f32_e32 v193, 1.0, v193
	v_add_f32_e32 v194, 1.0, v194
	v_add_f32_e32 v195, 1.0, v195
	v_add_f32_e32 v196, 1.0, v196
	v_add_f32_e32 v197, 1.0, v197
	v_rcp_f32_e32 v190, v190
	v_rcp_f32_e32 v191, v191
	v_rcp_f32_e32 v192, v192
	v_rcp_f32_e32 v193, v193
	v_rcp_f32_e32 v194, v194
	v_rcp_f32_e32 v195, v195
	v_rcp_f32_e32 v196, v196
	v_rcp_f32_e32 v197, v197
	v_mul_f32_e32 v142, v142, v190
	v_mul_f32_e32 v143, v143, v191
	v_mul_f32_e32 v144, v144, v192
	v_mul_f32_e32 v145, v145, v193
	v_mul_f32_e32 v138, v138, v194
	v_mul_f32_e32 v139, v139, v195
	v_mul_f32_e32 v140, v140, v196
	v_mul_f32_e32 v141, v141, v197
	v_mul_f32_e32 v190, v142, v142
	v_mul_f32_e32 v191, v144, v144
	v_mul_f32_e32 v192, v138, v138
	v_mul_f32_e32 v193, v140, v140
	v_fmac_f32_e32 v190, v143, v143
	v_fmac_f32_e32 v191, v145, v145
	v_fmac_f32_e32 v192, v139, v139
	v_fmac_f32_e32 v193, v141, v141
	v_cvt_pk_bf16_f32 v198, v142, v143
	v_cvt_pk_bf16_f32 v199, v144, v145
	v_cvt_pk_bf16_f32 v200, v138, v139
	v_cvt_pk_bf16_f32 v201, v140, v141
	v_add_f32_e32 v190, v190, v191
	v_add_f32_e32 v192, v192, v193
	v_add_f32_e32 v190, v190, v192
	v_mov_b32_e32 v168, v190
	global_store_dwordx4 v[228:229], v[198:201], off
	v_fma_f32 v134, v134, v214, v38
	v_fma_f32 v135, v135, v214, v39
	v_fma_f32 v136, v136, v214, v40
	v_fma_f32 v137, v137, v214, v41
	v_fma_f32 v130, v130, v214, v34
	v_fma_f32 v131, v131, v214, v35
	v_fma_f32 v132, v132, v214, v36
	v_fma_f32 v133, v133, v214, v37
	v_mul_f32_e32 v190, v134, v134
	v_mul_f32_e32 v191, v135, v135
	v_mul_f32_e32 v192, v136, v136
	v_mul_f32_e32 v193, v137, v137
	v_mul_f32_e32 v194, v130, v130
	v_mul_f32_e32 v195, v131, v131
	v_mul_f32_e32 v196, v132, v132
	v_mul_f32_e32 v197, v133, v133
	v_fmaak_f32 v190, v190, v170, 0xc0135761
	v_fmaak_f32 v191, v191, v170, 0xc0135761
	v_fmaak_f32 v192, v192, v170, 0xc0135761
	v_fmaak_f32 v193, v193, v170, 0xc0135761
	v_fmaak_f32 v194, v194, v170, 0xc0135761
	v_fmaak_f32 v195, v195, v170, 0xc0135761
	v_fmaak_f32 v196, v196, v170, 0xc0135761
	v_fmaak_f32 v197, v197, v170, 0xc0135761
	v_mul_f32_e32 v190, v190, v134
	v_mul_f32_e32 v191, v191, v135
	v_mul_f32_e32 v192, v192, v136
	v_mul_f32_e32 v193, v193, v137
	v_mul_f32_e32 v194, v194, v130
	v_mul_f32_e32 v195, v195, v131
	v_mul_f32_e32 v196, v196, v132
	v_mul_f32_e32 v197, v197, v133
	v_exp_f32_e32 v190, v190
	v_exp_f32_e32 v191, v191
	v_exp_f32_e32 v192, v192
	v_exp_f32_e32 v193, v193
	v_exp_f32_e32 v194, v194
	v_exp_f32_e32 v195, v195
	v_exp_f32_e32 v196, v196
	v_exp_f32_e32 v197, v197
	v_add_f32_e32 v190, 1.0, v190
	v_add_f32_e32 v191, 1.0, v191
	v_add_f32_e32 v192, 1.0, v192
	v_add_f32_e32 v193, 1.0, v193
	v_add_f32_e32 v194, 1.0, v194
	v_add_f32_e32 v195, 1.0, v195
	v_add_f32_e32 v196, 1.0, v196
	v_add_f32_e32 v197, 1.0, v197
	v_rcp_f32_e32 v190, v190
	v_rcp_f32_e32 v191, v191
	v_rcp_f32_e32 v192, v192
	v_rcp_f32_e32 v193, v193
	v_rcp_f32_e32 v194, v194
	v_rcp_f32_e32 v195, v195
	v_rcp_f32_e32 v196, v196
	v_rcp_f32_e32 v197, v197
	v_mul_f32_e32 v134, v134, v190
	v_mul_f32_e32 v135, v135, v191
	v_mul_f32_e32 v136, v136, v192
	v_mul_f32_e32 v137, v137, v193
	v_mul_f32_e32 v130, v130, v194
	v_mul_f32_e32 v131, v131, v195
	v_mul_f32_e32 v132, v132, v196
	v_mul_f32_e32 v133, v133, v197
	v_mul_f32_e32 v190, v134, v134
	v_mul_f32_e32 v191, v136, v136
	v_mul_f32_e32 v192, v130, v130
	v_mul_f32_e32 v193, v132, v132
	v_fmac_f32_e32 v190, v135, v135
	v_fmac_f32_e32 v191, v137, v137
	v_fmac_f32_e32 v192, v131, v131
	v_fmac_f32_e32 v193, v133, v133
	v_cvt_pk_bf16_f32 v202, v134, v135
	v_cvt_pk_bf16_f32 v203, v136, v137
	v_cvt_pk_bf16_f32 v204, v130, v131
	v_cvt_pk_bf16_f32 v205, v132, v133
	v_add_f32_e32 v190, v190, v191
	v_add_f32_e32 v192, v192, v193
	v_add_f32_e32 v190, v190, v192
	v_add_f32_e32 v168, v168, v190
	global_store_dwordx4 v[228:229], v[202:205], off offset:256
	s_cmp_lg_u32 s10, 4
	s_cbranch_scc1 .Lwin_noat_l0_0
	ds_bpermute_b32 v171, v224, v168
	v_ashrrev_i32_e32 v173, 31, v169
	v_mov_b32_e32 v172, v169
	s_waitcnt lgkmcnt(0)
	v_add_f32_e32 v168, v168, v171
	ds_bpermute_b32 v171, v225, v168
	v_lshl_add_u64 v[172:173], v[172:173], 2, s[48:49]
	s_waitcnt lgkmcnt(0)
	v_add_f32_e32 v168, v168, v171
	s_mov_b64 s[84:85], exec
	s_and_b64 exec, exec, s[0:1]
	global_atomic_add_f32 v[172:173], v168, off
	s_mov_b64 exec, s[84:85]
.Lwin_noat_l0_0:
	v_fma_f32 v126, v126, v215, v42
	v_fma_f32 v127, v127, v215, v43
	v_fma_f32 v128, v128, v215, v44
	v_fma_f32 v129, v129, v215, v45
	v_fma_f32 v122, v122, v215, v46
	v_fma_f32 v123, v123, v215, v47
	v_fma_f32 v124, v124, v215, v48
	v_fma_f32 v125, v125, v215, v49
	v_mul_f32_e32 v190, v126, v126
	v_mul_f32_e32 v191, v127, v127
	v_mul_f32_e32 v192, v128, v128
	v_mul_f32_e32 v193, v129, v129
	v_mul_f32_e32 v194, v122, v122
	v_mul_f32_e32 v195, v123, v123
	v_mul_f32_e32 v196, v124, v124
	v_mul_f32_e32 v197, v125, v125
	v_fmaak_f32 v190, v190, v170, 0xc0135761
	v_fmaak_f32 v191, v191, v170, 0xc0135761
	v_fmaak_f32 v192, v192, v170, 0xc0135761
	v_fmaak_f32 v193, v193, v170, 0xc0135761
	v_fmaak_f32 v194, v194, v170, 0xc0135761
	v_fmaak_f32 v195, v195, v170, 0xc0135761
	v_fmaak_f32 v196, v196, v170, 0xc0135761
	v_fmaak_f32 v197, v197, v170, 0xc0135761
	v_add_u32_e32 v169, s23, v176
	v_mad_i64_i32 v[166:167], s[8:9], v169, s22, v[226:227]
	v_mul_f32_e32 v190, v190, v126
	v_mul_f32_e32 v191, v191, v127
	v_mul_f32_e32 v192, v192, v128
	v_mul_f32_e32 v193, v193, v129
	v_mul_f32_e32 v194, v194, v122
	v_mul_f32_e32 v195, v195, v123
	v_mul_f32_e32 v196, v196, v124
	v_mul_f32_e32 v197, v197, v125
	v_exp_f32_e32 v190, v190
	v_exp_f32_e32 v191, v191
	v_exp_f32_e32 v192, v192
	v_exp_f32_e32 v193, v193
	v_exp_f32_e32 v194, v194
	v_exp_f32_e32 v195, v195
	v_exp_f32_e32 v196, v196
	v_exp_f32_e32 v197, v197
	v_add_f32_e32 v190, 1.0, v190
	v_add_f32_e32 v191, 1.0, v191
	v_add_f32_e32 v192, 1.0, v192
	v_add_f32_e32 v193, 1.0, v193
	v_add_f32_e32 v194, 1.0, v194
	v_add_f32_e32 v195, 1.0, v195
	v_add_f32_e32 v196, 1.0, v196
	v_add_f32_e32 v197, 1.0, v197
	v_rcp_f32_e32 v190, v190
	v_rcp_f32_e32 v191, v191
	v_rcp_f32_e32 v192, v192
	v_rcp_f32_e32 v193, v193
	v_rcp_f32_e32 v194, v194
	v_rcp_f32_e32 v195, v195
	v_rcp_f32_e32 v196, v196
	v_rcp_f32_e32 v197, v197
	v_mul_f32_e32 v126, v126, v190
	v_mul_f32_e32 v127, v127, v191
	v_mul_f32_e32 v128, v128, v192
	v_mul_f32_e32 v129, v129, v193
	v_mul_f32_e32 v122, v122, v194
	v_mul_f32_e32 v123, v123, v195
	v_mul_f32_e32 v124, v124, v196
	v_mul_f32_e32 v125, v125, v197
	v_mul_f32_e32 v190, v126, v126
	v_mul_f32_e32 v191, v128, v128
	v_mul_f32_e32 v192, v122, v122
	v_mul_f32_e32 v193, v124, v124
	v_fmac_f32_e32 v190, v127, v127
	v_fmac_f32_e32 v191, v129, v129
	v_fmac_f32_e32 v192, v123, v123
	v_fmac_f32_e32 v193, v125, v125
	v_cvt_pk_bf16_f32 v206, v126, v127
	v_cvt_pk_bf16_f32 v207, v128, v129
	v_cvt_pk_bf16_f32 v208, v122, v123
	v_cvt_pk_bf16_f32 v209, v124, v125
	v_add_f32_e32 v190, v190, v191
	v_add_f32_e32 v192, v192, v193
	v_add_f32_e32 v190, v190, v192
	v_mov_b32_e32 v168, v190
	global_store_dwordx4 v[166:167], v[206:209], off
	v_fma_f32 v118, v118, v215, v38
	v_fma_f32 v119, v119, v215, v39
	v_fma_f32 v120, v120, v215, v40
	v_fma_f32 v121, v121, v215, v41
	v_fma_f32 v114, v114, v215, v34
	v_fma_f32 v115, v115, v215, v35
	v_fma_f32 v116, v116, v215, v36
	v_fma_f32 v117, v117, v215, v37
	v_mul_f32_e32 v190, v118, v118
	v_mul_f32_e32 v191, v119, v119
	v_mul_f32_e32 v192, v120, v120
	v_mul_f32_e32 v193, v121, v121
	v_mul_f32_e32 v194, v114, v114
	v_mul_f32_e32 v195, v115, v115
	v_mul_f32_e32 v196, v116, v116
	v_mul_f32_e32 v197, v117, v117
	v_fmaak_f32 v190, v190, v170, 0xc0135761
	v_fmaak_f32 v191, v191, v170, 0xc0135761
	v_fmaak_f32 v192, v192, v170, 0xc0135761
	v_fmaak_f32 v193, v193, v170, 0xc0135761
	v_fmaak_f32 v194, v194, v170, 0xc0135761
	v_fmaak_f32 v195, v195, v170, 0xc0135761
	v_fmaak_f32 v196, v196, v170, 0xc0135761
	v_fmaak_f32 v197, v197, v170, 0xc0135761
	v_mul_f32_e32 v190, v190, v118
	v_mul_f32_e32 v191, v191, v119
	v_mul_f32_e32 v192, v192, v120
	v_mul_f32_e32 v193, v193, v121
	v_mul_f32_e32 v194, v194, v114
	v_mul_f32_e32 v195, v195, v115
	v_mul_f32_e32 v196, v196, v116
	v_mul_f32_e32 v197, v197, v117
	v_exp_f32_e32 v190, v190
	v_exp_f32_e32 v191, v191
	v_exp_f32_e32 v192, v192
	v_exp_f32_e32 v193, v193
	v_exp_f32_e32 v194, v194
	v_exp_f32_e32 v195, v195
	v_exp_f32_e32 v196, v196
	v_exp_f32_e32 v197, v197
	v_add_f32_e32 v190, 1.0, v190
	v_add_f32_e32 v191, 1.0, v191
	v_add_f32_e32 v192, 1.0, v192
	v_add_f32_e32 v193, 1.0, v193
	v_add_f32_e32 v194, 1.0, v194
	v_add_f32_e32 v195, 1.0, v195
	v_add_f32_e32 v196, 1.0, v196
	v_add_f32_e32 v197, 1.0, v197
	v_rcp_f32_e32 v190, v190
	v_rcp_f32_e32 v191, v191
	v_rcp_f32_e32 v192, v192
	v_rcp_f32_e32 v193, v193
	v_rcp_f32_e32 v194, v194
	v_rcp_f32_e32 v195, v195
	v_rcp_f32_e32 v196, v196
	v_rcp_f32_e32 v197, v197
	v_mul_f32_e32 v118, v118, v190
	v_mul_f32_e32 v119, v119, v191
	v_mul_f32_e32 v120, v120, v192
	v_mul_f32_e32 v121, v121, v193
	v_mul_f32_e32 v114, v114, v194
	v_mul_f32_e32 v115, v115, v195
	v_mul_f32_e32 v116, v116, v196
	v_mul_f32_e32 v117, v117, v197
	v_mul_f32_e32 v190, v118, v118
	v_mul_f32_e32 v191, v120, v120
	v_mul_f32_e32 v192, v114, v114
	v_mul_f32_e32 v193, v116, v116
	v_fmac_f32_e32 v190, v119, v119
	v_fmac_f32_e32 v191, v121, v121
	v_fmac_f32_e32 v192, v115, v115
	v_fmac_f32_e32 v193, v117, v117
	v_cvt_pk_bf16_f32 v210, v118, v119
	v_cvt_pk_bf16_f32 v211, v120, v121
	v_cvt_pk_bf16_f32 v212, v114, v115
	v_cvt_pk_bf16_f32 v213, v116, v117
	v_add_f32_e32 v190, v190, v191
	v_add_f32_e32 v192, v192, v193
	v_add_f32_e32 v190, v190, v192
	v_add_f32_e32 v168, v168, v190
	global_store_dwordx4 v[166:167], v[210:213], off offset:256
	s_cmp_lg_u32 s10, 4
	s_cbranch_scc1 .Lwin_noat_l0_1
	ds_bpermute_b32 v171, v224, v168
	v_ashrrev_i32_e32 v173, 31, v169
	v_mov_b32_e32 v172, v169
	s_waitcnt lgkmcnt(0)
	v_add_f32_e32 v168, v168, v171
	ds_bpermute_b32 v171, v225, v168
	v_lshl_add_u64 v[172:173], v[172:173], 2, s[48:49]
	s_waitcnt lgkmcnt(0)
	v_add_f32_e32 v168, v168, v171
	s_mov_b64 s[84:85], exec
	s_and_b64 exec, exec, s[0:1]
	global_atomic_add_f32 v[172:173], v168, off
	s_mov_b64 exec, s[84:85]
.Lwin_noat_l0_1:
	v_fma_f32 v110, v110, v216, v42
	v_fma_f32 v111, v111, v216, v43
	v_fma_f32 v112, v112, v216, v44
	v_fma_f32 v113, v113, v216, v45
	v_fma_f32 v106, v106, v216, v46
	v_fma_f32 v107, v107, v216, v47
	v_fma_f32 v108, v108, v216, v48
	v_fma_f32 v109, v109, v216, v49
	v_mul_f32_e32 v190, v110, v110
	v_mul_f32_e32 v191, v111, v111
	v_mul_f32_e32 v192, v112, v112
	v_mul_f32_e32 v193, v113, v113
	v_mul_f32_e32 v194, v106, v106
	v_mul_f32_e32 v195, v107, v107
	v_mul_f32_e32 v196, v108, v108
	v_mul_f32_e32 v197, v109, v109
	v_fmaak_f32 v190, v190, v170, 0xc0135761
	v_fmaak_f32 v191, v191, v170, 0xc0135761
	v_fmaak_f32 v192, v192, v170, 0xc0135761
	v_fmaak_f32 v193, v193, v170, 0xc0135761
	v_fmaak_f32 v194, v194, v170, 0xc0135761
	v_fmaak_f32 v195, v195, v170, 0xc0135761
	v_fmaak_f32 v196, v196, v170, 0xc0135761
	v_fmaak_f32 v197, v197, v170, 0xc0135761
	v_add_u32_e32 v169, s23, v177
	v_mad_i64_i32 v[228:229], s[8:9], v169, s22, v[226:227]
	v_mul_f32_e32 v190, v190, v110
	v_mul_f32_e32 v191, v191, v111
	v_mul_f32_e32 v192, v192, v112
	v_mul_f32_e32 v193, v193, v113
	v_mul_f32_e32 v194, v194, v106
	v_mul_f32_e32 v195, v195, v107
	v_mul_f32_e32 v196, v196, v108
	v_mul_f32_e32 v197, v197, v109
	v_exp_f32_e32 v190, v190
	v_exp_f32_e32 v191, v191
	v_exp_f32_e32 v192, v192
	v_exp_f32_e32 v193, v193
	v_exp_f32_e32 v194, v194
	v_exp_f32_e32 v195, v195
	v_exp_f32_e32 v196, v196
	v_exp_f32_e32 v197, v197
	v_add_f32_e32 v190, 1.0, v190
	v_add_f32_e32 v191, 1.0, v191
	v_add_f32_e32 v192, 1.0, v192
	v_add_f32_e32 v193, 1.0, v193
	v_add_f32_e32 v194, 1.0, v194
	v_add_f32_e32 v195, 1.0, v195
	v_add_f32_e32 v196, 1.0, v196
	v_add_f32_e32 v197, 1.0, v197
	v_rcp_f32_e32 v190, v190
	v_rcp_f32_e32 v191, v191
	v_rcp_f32_e32 v192, v192
	v_rcp_f32_e32 v193, v193
	v_rcp_f32_e32 v194, v194
	v_rcp_f32_e32 v195, v195
	v_rcp_f32_e32 v196, v196
	v_rcp_f32_e32 v197, v197
	v_mul_f32_e32 v110, v110, v190
	v_mul_f32_e32 v111, v111, v191
	v_mul_f32_e32 v112, v112, v192
	v_mul_f32_e32 v113, v113, v193
	v_mul_f32_e32 v106, v106, v194
	v_mul_f32_e32 v107, v107, v195
	v_mul_f32_e32 v108, v108, v196
	v_mul_f32_e32 v109, v109, v197
	v_mul_f32_e32 v190, v110, v110
	v_mul_f32_e32 v191, v112, v112
	v_mul_f32_e32 v192, v106, v106
	v_mul_f32_e32 v193, v108, v108
	v_fmac_f32_e32 v190, v111, v111
	v_fmac_f32_e32 v191, v113, v113
	v_fmac_f32_e32 v192, v107, v107
	v_fmac_f32_e32 v193, v109, v109
	v_cvt_pk_bf16_f32 v198, v110, v111
	v_cvt_pk_bf16_f32 v199, v112, v113
	v_cvt_pk_bf16_f32 v200, v106, v107
	v_cvt_pk_bf16_f32 v201, v108, v109
	v_add_f32_e32 v190, v190, v191
	v_add_f32_e32 v192, v192, v193
	v_add_f32_e32 v190, v190, v192
	v_mov_b32_e32 v168, v190
	global_store_dwordx4 v[228:229], v[198:201], off
	v_fma_f32 v102, v102, v216, v38
	v_fma_f32 v103, v103, v216, v39
	v_fma_f32 v104, v104, v216, v40
	v_fma_f32 v105, v105, v216, v41
	v_fma_f32 v98, v98, v216, v34
	v_fma_f32 v99, v99, v216, v35
	v_fma_f32 v100, v100, v216, v36
	v_fma_f32 v101, v101, v216, v37
	v_mul_f32_e32 v190, v102, v102
	v_mul_f32_e32 v191, v103, v103
	v_mul_f32_e32 v192, v104, v104
	v_mul_f32_e32 v193, v105, v105
	v_mul_f32_e32 v194, v98, v98
	v_mul_f32_e32 v195, v99, v99
	v_mul_f32_e32 v196, v100, v100
	v_mul_f32_e32 v197, v101, v101
	v_fmaak_f32 v190, v190, v170, 0xc0135761
	v_fmaak_f32 v191, v191, v170, 0xc0135761
	v_fmaak_f32 v192, v192, v170, 0xc0135761
	v_fmaak_f32 v193, v193, v170, 0xc0135761
	v_fmaak_f32 v194, v194, v170, 0xc0135761
	v_fmaak_f32 v195, v195, v170, 0xc0135761
	v_fmaak_f32 v196, v196, v170, 0xc0135761
	v_fmaak_f32 v197, v197, v170, 0xc0135761
	v_mul_f32_e32 v190, v190, v102
	v_mul_f32_e32 v191, v191, v103
	v_mul_f32_e32 v192, v192, v104
	v_mul_f32_e32 v193, v193, v105
	v_mul_f32_e32 v194, v194, v98
	v_mul_f32_e32 v195, v195, v99
	v_mul_f32_e32 v196, v196, v100
	v_mul_f32_e32 v197, v197, v101
	v_exp_f32_e32 v190, v190
	v_exp_f32_e32 v191, v191
	v_exp_f32_e32 v192, v192
	v_exp_f32_e32 v193, v193
	v_exp_f32_e32 v194, v194
	v_exp_f32_e32 v195, v195
	v_exp_f32_e32 v196, v196
	v_exp_f32_e32 v197, v197
	v_add_f32_e32 v190, 1.0, v190
	v_add_f32_e32 v191, 1.0, v191
	v_add_f32_e32 v192, 1.0, v192
	v_add_f32_e32 v193, 1.0, v193
	v_add_f32_e32 v194, 1.0, v194
	v_add_f32_e32 v195, 1.0, v195
	v_add_f32_e32 v196, 1.0, v196
	v_add_f32_e32 v197, 1.0, v197
	v_rcp_f32_e32 v190, v190
	v_rcp_f32_e32 v191, v191
	v_rcp_f32_e32 v192, v192
	v_rcp_f32_e32 v193, v193
	v_rcp_f32_e32 v194, v194
	v_rcp_f32_e32 v195, v195
	v_rcp_f32_e32 v196, v196
	v_rcp_f32_e32 v197, v197
	v_mul_f32_e32 v102, v102, v190
	v_mul_f32_e32 v103, v103, v191
	v_mul_f32_e32 v104, v104, v192
	v_mul_f32_e32 v105, v105, v193
	v_mul_f32_e32 v98, v98, v194
	v_mul_f32_e32 v99, v99, v195
	v_mul_f32_e32 v100, v100, v196
	v_mul_f32_e32 v101, v101, v197
	v_mul_f32_e32 v190, v102, v102
	v_mul_f32_e32 v191, v104, v104
	v_mul_f32_e32 v192, v98, v98
	v_mul_f32_e32 v193, v100, v100
	v_fmac_f32_e32 v190, v103, v103
	v_fmac_f32_e32 v191, v105, v105
	v_fmac_f32_e32 v192, v99, v99
	v_fmac_f32_e32 v193, v101, v101
	v_cvt_pk_bf16_f32 v202, v102, v103
	v_cvt_pk_bf16_f32 v203, v104, v105
	v_cvt_pk_bf16_f32 v204, v98, v99
	v_cvt_pk_bf16_f32 v205, v100, v101
	v_add_f32_e32 v190, v190, v191
	v_add_f32_e32 v192, v192, v193
	v_add_f32_e32 v190, v190, v192
	v_add_f32_e32 v168, v168, v190
	global_store_dwordx4 v[228:229], v[202:205], off offset:256
	s_cmp_lg_u32 s10, 4
	s_cbranch_scc1 .Lwin_noat_l0_2
	ds_bpermute_b32 v171, v224, v168
	v_ashrrev_i32_e32 v173, 31, v169
	v_mov_b32_e32 v172, v169
	s_waitcnt lgkmcnt(0)
	v_add_f32_e32 v168, v168, v171
	ds_bpermute_b32 v171, v225, v168
	v_lshl_add_u64 v[172:173], v[172:173], 2, s[48:49]
	s_waitcnt lgkmcnt(0)
	v_add_f32_e32 v168, v168, v171
	s_mov_b64 s[84:85], exec
	s_and_b64 exec, exec, s[0:1]
	global_atomic_add_f32 v[172:173], v168, off
	s_mov_b64 exec, s[84:85]
.Lwin_noat_l0_2:
	v_fma_f32 v94, v94, v217, v42
	v_fma_f32 v95, v95, v217, v43
	v_fma_f32 v96, v96, v217, v44
	v_fma_f32 v97, v97, v217, v45
	v_fma_f32 v90, v90, v217, v46
	v_fma_f32 v91, v91, v217, v47
	v_fma_f32 v92, v92, v217, v48
	v_fma_f32 v93, v93, v217, v49
	v_mul_f32_e32 v190, v94, v94
	v_mul_f32_e32 v191, v95, v95
	v_mul_f32_e32 v192, v96, v96
	v_mul_f32_e32 v193, v97, v97
	v_mul_f32_e32 v194, v90, v90
	v_mul_f32_e32 v195, v91, v91
	v_mul_f32_e32 v196, v92, v92
	v_mul_f32_e32 v197, v93, v93
	v_fmaak_f32 v190, v190, v170, 0xc0135761
	v_fmaak_f32 v191, v191, v170, 0xc0135761
	v_fmaak_f32 v192, v192, v170, 0xc0135761
	v_fmaak_f32 v193, v193, v170, 0xc0135761
	v_fmaak_f32 v194, v194, v170, 0xc0135761
	v_fmaak_f32 v195, v195, v170, 0xc0135761
	v_fmaak_f32 v196, v196, v170, 0xc0135761
	v_fmaak_f32 v197, v197, v170, 0xc0135761
	v_add_u32_e32 v169, s23, v178
	v_mad_i64_i32 v[166:167], s[8:9], v169, s22, v[226:227]
	v_mul_f32_e32 v190, v190, v94
	v_mul_f32_e32 v191, v191, v95
	v_mul_f32_e32 v192, v192, v96
	v_mul_f32_e32 v193, v193, v97
	v_mul_f32_e32 v194, v194, v90
	v_mul_f32_e32 v195, v195, v91
	v_mul_f32_e32 v196, v196, v92
	v_mul_f32_e32 v197, v197, v93
	v_exp_f32_e32 v190, v190
	v_exp_f32_e32 v191, v191
	v_exp_f32_e32 v192, v192
	v_exp_f32_e32 v193, v193
	v_exp_f32_e32 v194, v194
	v_exp_f32_e32 v195, v195
	v_exp_f32_e32 v196, v196
	v_exp_f32_e32 v197, v197
	v_add_f32_e32 v190, 1.0, v190
	v_add_f32_e32 v191, 1.0, v191
	v_add_f32_e32 v192, 1.0, v192
	v_add_f32_e32 v193, 1.0, v193
	v_add_f32_e32 v194, 1.0, v194
	v_add_f32_e32 v195, 1.0, v195
	v_add_f32_e32 v196, 1.0, v196
	v_add_f32_e32 v197, 1.0, v197
	v_rcp_f32_e32 v190, v190
	v_rcp_f32_e32 v191, v191
	v_rcp_f32_e32 v192, v192
	v_rcp_f32_e32 v193, v193
	v_rcp_f32_e32 v194, v194
	v_rcp_f32_e32 v195, v195
	v_rcp_f32_e32 v196, v196
	v_rcp_f32_e32 v197, v197
	v_mul_f32_e32 v94, v94, v190
	v_mul_f32_e32 v95, v95, v191
	v_mul_f32_e32 v96, v96, v192
	v_mul_f32_e32 v97, v97, v193
	v_mul_f32_e32 v90, v90, v194
	v_mul_f32_e32 v91, v91, v195
	v_mul_f32_e32 v92, v92, v196
	v_mul_f32_e32 v93, v93, v197
	v_mul_f32_e32 v190, v94, v94
	v_mul_f32_e32 v191, v96, v96
	v_mul_f32_e32 v192, v90, v90
	v_mul_f32_e32 v193, v92, v92
	v_fmac_f32_e32 v190, v95, v95
	v_fmac_f32_e32 v191, v97, v97
	v_fmac_f32_e32 v192, v91, v91
	v_fmac_f32_e32 v193, v93, v93
	v_cvt_pk_bf16_f32 v206, v94, v95
	v_cvt_pk_bf16_f32 v207, v96, v97
	v_cvt_pk_bf16_f32 v208, v90, v91
	v_cvt_pk_bf16_f32 v209, v92, v93
	v_add_f32_e32 v190, v190, v191
	v_add_f32_e32 v192, v192, v193
	v_add_f32_e32 v190, v190, v192
	v_mov_b32_e32 v168, v190
	global_store_dwordx4 v[166:167], v[206:209], off
	v_fma_f32 v86, v86, v217, v38
	v_fma_f32 v87, v87, v217, v39
	v_fma_f32 v88, v88, v217, v40
	v_fma_f32 v89, v89, v217, v41
	v_fma_f32 v82, v82, v217, v34
	v_fma_f32 v83, v83, v217, v35
	v_fma_f32 v84, v84, v217, v36
	v_fma_f32 v85, v85, v217, v37
	v_mul_f32_e32 v190, v86, v86
	v_mul_f32_e32 v191, v87, v87
	v_mul_f32_e32 v192, v88, v88
	v_mul_f32_e32 v193, v89, v89
	v_mul_f32_e32 v194, v82, v82
	v_mul_f32_e32 v195, v83, v83
	v_mul_f32_e32 v196, v84, v84
	v_mul_f32_e32 v197, v85, v85
	v_fmaak_f32 v190, v190, v170, 0xc0135761
	v_fmaak_f32 v191, v191, v170, 0xc0135761
	v_fmaak_f32 v192, v192, v170, 0xc0135761
	v_fmaak_f32 v193, v193, v170, 0xc0135761
	v_fmaak_f32 v194, v194, v170, 0xc0135761
	v_fmaak_f32 v195, v195, v170, 0xc0135761
	v_fmaak_f32 v196, v196, v170, 0xc0135761
	v_fmaak_f32 v197, v197, v170, 0xc0135761
	v_mul_f32_e32 v190, v190, v86
	v_mul_f32_e32 v191, v191, v87
	v_mul_f32_e32 v192, v192, v88
	v_mul_f32_e32 v193, v193, v89
	v_mul_f32_e32 v194, v194, v82
	v_mul_f32_e32 v195, v195, v83
	v_mul_f32_e32 v196, v196, v84
	v_mul_f32_e32 v197, v197, v85
	v_exp_f32_e32 v190, v190
	v_exp_f32_e32 v191, v191
	v_exp_f32_e32 v192, v192
	v_exp_f32_e32 v193, v193
	v_exp_f32_e32 v194, v194
	v_exp_f32_e32 v195, v195
	v_exp_f32_e32 v196, v196
	v_exp_f32_e32 v197, v197
	v_add_f32_e32 v190, 1.0, v190
	v_add_f32_e32 v191, 1.0, v191
	v_add_f32_e32 v192, 1.0, v192
	v_add_f32_e32 v193, 1.0, v193
	v_add_f32_e32 v194, 1.0, v194
	v_add_f32_e32 v195, 1.0, v195
	v_add_f32_e32 v196, 1.0, v196
	v_add_f32_e32 v197, 1.0, v197
	v_rcp_f32_e32 v190, v190
	v_rcp_f32_e32 v191, v191
	v_rcp_f32_e32 v192, v192
	v_rcp_f32_e32 v193, v193
	v_rcp_f32_e32 v194, v194
	v_rcp_f32_e32 v195, v195
	v_rcp_f32_e32 v196, v196
	v_rcp_f32_e32 v197, v197
	v_mul_f32_e32 v86, v86, v190
	v_mul_f32_e32 v87, v87, v191
	v_mul_f32_e32 v88, v88, v192
	v_mul_f32_e32 v89, v89, v193
	v_mul_f32_e32 v82, v82, v194
	v_mul_f32_e32 v83, v83, v195
	v_mul_f32_e32 v84, v84, v196
	v_mul_f32_e32 v85, v85, v197
	v_mul_f32_e32 v190, v86, v86
	v_mul_f32_e32 v191, v88, v88
	v_mul_f32_e32 v192, v82, v82
	v_mul_f32_e32 v193, v84, v84
	v_fmac_f32_e32 v190, v87, v87
	v_fmac_f32_e32 v191, v89, v89
	v_fmac_f32_e32 v192, v83, v83
	v_fmac_f32_e32 v193, v85, v85
	v_cvt_pk_bf16_f32 v210, v86, v87
	v_cvt_pk_bf16_f32 v211, v88, v89
	v_cvt_pk_bf16_f32 v212, v82, v83
	v_cvt_pk_bf16_f32 v213, v84, v85
	v_add_f32_e32 v190, v190, v191
	v_add_f32_e32 v192, v192, v193
	v_add_f32_e32 v190, v190, v192
	v_add_f32_e32 v168, v168, v190
	global_store_dwordx4 v[166:167], v[210:213], off offset:256
	s_cmp_lg_u32 s10, 4
	s_cbranch_scc1 .Lwin_noat_l0_3
	ds_bpermute_b32 v171, v224, v168
	v_ashrrev_i32_e32 v173, 31, v169
	v_mov_b32_e32 v172, v169
	s_waitcnt lgkmcnt(0)
	v_add_f32_e32 v168, v168, v171
	ds_bpermute_b32 v171, v225, v168
	v_lshl_add_u64 v[172:173], v[172:173], 2, s[48:49]
	s_waitcnt lgkmcnt(0)
	v_add_f32_e32 v168, v168, v171
	s_mov_b64 s[84:85], exec
	s_and_b64 exec, exec, s[0:1]
	global_atomic_add_f32 v[172:173], v168, off
	s_mov_b64 exec, s[84:85]
.Lwin_noat_l0_3:
	v_fma_f32 v78, v78, v218, v42
	v_fma_f32 v79, v79, v218, v43
	v_fma_f32 v80, v80, v218, v44
	v_fma_f32 v81, v81, v218, v45
	v_fma_f32 v74, v74, v218, v46
	v_fma_f32 v75, v75, v218, v47
	v_fma_f32 v76, v76, v218, v48
	v_fma_f32 v77, v77, v218, v49
	v_mul_f32_e32 v190, v78, v78
	v_mul_f32_e32 v191, v79, v79
	v_mul_f32_e32 v192, v80, v80
	v_mul_f32_e32 v193, v81, v81
	v_mul_f32_e32 v194, v74, v74
	v_mul_f32_e32 v195, v75, v75
	v_mul_f32_e32 v196, v76, v76
	v_mul_f32_e32 v197, v77, v77
	v_fmaak_f32 v190, v190, v170, 0xc0135761
	v_fmaak_f32 v191, v191, v170, 0xc0135761
	v_fmaak_f32 v192, v192, v170, 0xc0135761
	v_fmaak_f32 v193, v193, v170, 0xc0135761
	v_fmaak_f32 v194, v194, v170, 0xc0135761
	v_fmaak_f32 v195, v195, v170, 0xc0135761
	v_fmaak_f32 v196, v196, v170, 0xc0135761
	v_fmaak_f32 v197, v197, v170, 0xc0135761
	v_add_u32_e32 v169, s23, v179
	v_mad_i64_i32 v[228:229], s[8:9], v169, s22, v[226:227]
	v_mul_f32_e32 v190, v190, v78
	v_mul_f32_e32 v191, v191, v79
	v_mul_f32_e32 v192, v192, v80
	v_mul_f32_e32 v193, v193, v81
	v_mul_f32_e32 v194, v194, v74
	v_mul_f32_e32 v195, v195, v75
	v_mul_f32_e32 v196, v196, v76
	v_mul_f32_e32 v197, v197, v77
	v_exp_f32_e32 v190, v190
	v_exp_f32_e32 v191, v191
	v_exp_f32_e32 v192, v192
	v_exp_f32_e32 v193, v193
	v_exp_f32_e32 v194, v194
	v_exp_f32_e32 v195, v195
	v_exp_f32_e32 v196, v196
	v_exp_f32_e32 v197, v197
	v_add_f32_e32 v190, 1.0, v190
	v_add_f32_e32 v191, 1.0, v191
	v_add_f32_e32 v192, 1.0, v192
	v_add_f32_e32 v193, 1.0, v193
	v_add_f32_e32 v194, 1.0, v194
	v_add_f32_e32 v195, 1.0, v195
	v_add_f32_e32 v196, 1.0, v196
	v_add_f32_e32 v197, 1.0, v197
	v_rcp_f32_e32 v190, v190
	v_rcp_f32_e32 v191, v191
	v_rcp_f32_e32 v192, v192
	v_rcp_f32_e32 v193, v193
	v_rcp_f32_e32 v194, v194
	v_rcp_f32_e32 v195, v195
	v_rcp_f32_e32 v196, v196
	v_rcp_f32_e32 v197, v197
	v_mul_f32_e32 v78, v78, v190
	v_mul_f32_e32 v79, v79, v191
	v_mul_f32_e32 v80, v80, v192
	v_mul_f32_e32 v81, v81, v193
	v_mul_f32_e32 v74, v74, v194
	v_mul_f32_e32 v75, v75, v195
	v_mul_f32_e32 v76, v76, v196
	v_mul_f32_e32 v77, v77, v197
	v_mul_f32_e32 v190, v78, v78
	v_mul_f32_e32 v191, v80, v80
	v_mul_f32_e32 v192, v74, v74
	v_mul_f32_e32 v193, v76, v76
	v_fmac_f32_e32 v190, v79, v79
	v_fmac_f32_e32 v191, v81, v81
	v_fmac_f32_e32 v192, v75, v75
	v_fmac_f32_e32 v193, v77, v77
	v_cvt_pk_bf16_f32 v198, v78, v79
	v_cvt_pk_bf16_f32 v199, v80, v81
	v_cvt_pk_bf16_f32 v200, v74, v75
	v_cvt_pk_bf16_f32 v201, v76, v77
	v_add_f32_e32 v190, v190, v191
	v_add_f32_e32 v192, v192, v193
	v_add_f32_e32 v190, v190, v192
	v_mov_b32_e32 v168, v190
	global_store_dwordx4 v[228:229], v[198:201], off
	v_fma_f32 v70, v70, v218, v38
	v_fma_f32 v71, v71, v218, v39
	v_fma_f32 v72, v72, v218, v40
	v_fma_f32 v73, v73, v218, v41
	v_fma_f32 v66, v66, v218, v34
	v_fma_f32 v67, v67, v218, v35
	v_fma_f32 v68, v68, v218, v36
	v_fma_f32 v69, v69, v218, v37
	v_mul_f32_e32 v190, v70, v70
	v_mul_f32_e32 v191, v71, v71
	v_mul_f32_e32 v192, v72, v72
	v_mul_f32_e32 v193, v73, v73
	v_mul_f32_e32 v194, v66, v66
	v_mul_f32_e32 v195, v67, v67
	v_mul_f32_e32 v196, v68, v68
	v_mul_f32_e32 v197, v69, v69
	v_fmaak_f32 v190, v190, v170, 0xc0135761
	v_fmaak_f32 v191, v191, v170, 0xc0135761
	v_fmaak_f32 v192, v192, v170, 0xc0135761
	v_fmaak_f32 v193, v193, v170, 0xc0135761
	v_fmaak_f32 v194, v194, v170, 0xc0135761
	v_fmaak_f32 v195, v195, v170, 0xc0135761
	v_fmaak_f32 v196, v196, v170, 0xc0135761
	v_fmaak_f32 v197, v197, v170, 0xc0135761
	v_mul_f32_e32 v190, v190, v70
	v_mul_f32_e32 v191, v191, v71
	v_mul_f32_e32 v192, v192, v72
	v_mul_f32_e32 v193, v193, v73
	v_mul_f32_e32 v194, v194, v66
	v_mul_f32_e32 v195, v195, v67
	v_mul_f32_e32 v196, v196, v68
	v_mul_f32_e32 v197, v197, v69
	v_exp_f32_e32 v190, v190
	v_exp_f32_e32 v191, v191
	v_exp_f32_e32 v192, v192
	v_exp_f32_e32 v193, v193
	v_exp_f32_e32 v194, v194
	v_exp_f32_e32 v195, v195
	v_exp_f32_e32 v196, v196
	v_exp_f32_e32 v197, v197
	v_add_f32_e32 v190, 1.0, v190
	v_add_f32_e32 v191, 1.0, v191
	v_add_f32_e32 v192, 1.0, v192
	v_add_f32_e32 v193, 1.0, v193
	v_add_f32_e32 v194, 1.0, v194
	v_add_f32_e32 v195, 1.0, v195
	v_add_f32_e32 v196, 1.0, v196
	v_add_f32_e32 v197, 1.0, v197
	v_rcp_f32_e32 v190, v190
	v_rcp_f32_e32 v191, v191
	v_rcp_f32_e32 v192, v192
	v_rcp_f32_e32 v193, v193
	v_rcp_f32_e32 v194, v194
	v_rcp_f32_e32 v195, v195
	v_rcp_f32_e32 v196, v196
	v_rcp_f32_e32 v197, v197
	v_mul_f32_e32 v70, v70, v190
	v_mul_f32_e32 v71, v71, v191
	v_mul_f32_e32 v72, v72, v192
	v_mul_f32_e32 v73, v73, v193
	v_mul_f32_e32 v66, v66, v194
	v_mul_f32_e32 v67, v67, v195
	v_mul_f32_e32 v68, v68, v196
	v_mul_f32_e32 v69, v69, v197
	v_mul_f32_e32 v190, v70, v70
	v_mul_f32_e32 v191, v72, v72
	v_mul_f32_e32 v192, v66, v66
	v_mul_f32_e32 v193, v68, v68
	v_fmac_f32_e32 v190, v71, v71
	v_fmac_f32_e32 v191, v73, v73
	v_fmac_f32_e32 v192, v67, v67
	v_fmac_f32_e32 v193, v69, v69
	v_cvt_pk_bf16_f32 v202, v70, v71
	v_cvt_pk_bf16_f32 v203, v72, v73
	v_cvt_pk_bf16_f32 v204, v66, v67
	v_cvt_pk_bf16_f32 v205, v68, v69
	v_add_f32_e32 v190, v190, v191
	v_add_f32_e32 v192, v192, v193
	v_add_f32_e32 v190, v190, v192
	v_add_f32_e32 v168, v168, v190
	global_store_dwordx4 v[228:229], v[202:205], off offset:256
	s_cmp_lg_u32 s10, 4
	s_cbranch_scc1 .Lwin_noat_l0_4
	ds_bpermute_b32 v171, v224, v168
	v_ashrrev_i32_e32 v173, 31, v169
	v_mov_b32_e32 v172, v169
	s_waitcnt lgkmcnt(0)
	v_add_f32_e32 v168, v168, v171
	ds_bpermute_b32 v171, v225, v168
	v_lshl_add_u64 v[172:173], v[172:173], 2, s[48:49]
	s_waitcnt lgkmcnt(0)
	v_add_f32_e32 v168, v168, v171
	s_mov_b64 s[84:85], exec
	s_and_b64 exec, exec, s[0:1]
	global_atomic_add_f32 v[172:173], v168, off
	s_mov_b64 exec, s[84:85]
.Lwin_noat_l0_4:
	v_fma_f32 v62, v62, v219, v42
	v_fma_f32 v63, v63, v219, v43
	v_fma_f32 v64, v64, v219, v44
	v_fma_f32 v65, v65, v219, v45
	v_fma_f32 v58, v58, v219, v46
	v_fma_f32 v59, v59, v219, v47
	v_fma_f32 v60, v60, v219, v48
	v_fma_f32 v61, v61, v219, v49
	v_mul_f32_e32 v190, v62, v62
	v_mul_f32_e32 v191, v63, v63
	v_mul_f32_e32 v192, v64, v64
	v_mul_f32_e32 v193, v65, v65
	v_mul_f32_e32 v194, v58, v58
	v_mul_f32_e32 v195, v59, v59
	v_mul_f32_e32 v196, v60, v60
	v_mul_f32_e32 v197, v61, v61
	v_fmaak_f32 v190, v190, v170, 0xc0135761
	v_fmaak_f32 v191, v191, v170, 0xc0135761
	v_fmaak_f32 v192, v192, v170, 0xc0135761
	v_fmaak_f32 v193, v193, v170, 0xc0135761
	v_fmaak_f32 v194, v194, v170, 0xc0135761
	v_fmaak_f32 v195, v195, v170, 0xc0135761
	v_fmaak_f32 v196, v196, v170, 0xc0135761
	v_fmaak_f32 v197, v197, v170, 0xc0135761
	v_add_u32_e32 v169, s23, v180
	v_mad_i64_i32 v[166:167], s[8:9], v169, s22, v[226:227]
	v_mul_f32_e32 v190, v190, v62
	v_mul_f32_e32 v191, v191, v63
	v_mul_f32_e32 v192, v192, v64
	v_mul_f32_e32 v193, v193, v65
	v_mul_f32_e32 v194, v194, v58
	v_mul_f32_e32 v195, v195, v59
	v_mul_f32_e32 v196, v196, v60
	v_mul_f32_e32 v197, v197, v61
	v_exp_f32_e32 v190, v190
	v_exp_f32_e32 v191, v191
	v_exp_f32_e32 v192, v192
	v_exp_f32_e32 v193, v193
	v_exp_f32_e32 v194, v194
	v_exp_f32_e32 v195, v195
	v_exp_f32_e32 v196, v196
	v_exp_f32_e32 v197, v197
	v_add_f32_e32 v190, 1.0, v190
	v_add_f32_e32 v191, 1.0, v191
	v_add_f32_e32 v192, 1.0, v192
	v_add_f32_e32 v193, 1.0, v193
	v_add_f32_e32 v194, 1.0, v194
	v_add_f32_e32 v195, 1.0, v195
	v_add_f32_e32 v196, 1.0, v196
	v_add_f32_e32 v197, 1.0, v197
	v_rcp_f32_e32 v190, v190
	v_rcp_f32_e32 v191, v191
	v_rcp_f32_e32 v192, v192
	v_rcp_f32_e32 v193, v193
	v_rcp_f32_e32 v194, v194
	v_rcp_f32_e32 v195, v195
	v_rcp_f32_e32 v196, v196
	v_rcp_f32_e32 v197, v197
	v_mul_f32_e32 v62, v62, v190
	v_mul_f32_e32 v63, v63, v191
	v_mul_f32_e32 v64, v64, v192
	v_mul_f32_e32 v65, v65, v193
	v_mul_f32_e32 v58, v58, v194
	v_mul_f32_e32 v59, v59, v195
	v_mul_f32_e32 v60, v60, v196
	v_mul_f32_e32 v61, v61, v197
	v_mul_f32_e32 v190, v62, v62
	v_mul_f32_e32 v191, v64, v64
	v_mul_f32_e32 v192, v58, v58
	v_mul_f32_e32 v193, v60, v60
	v_fmac_f32_e32 v190, v63, v63
	v_fmac_f32_e32 v191, v65, v65
	v_fmac_f32_e32 v192, v59, v59
	v_fmac_f32_e32 v193, v61, v61
	v_cvt_pk_bf16_f32 v206, v62, v63
	v_cvt_pk_bf16_f32 v207, v64, v65
	v_cvt_pk_bf16_f32 v208, v58, v59
	v_cvt_pk_bf16_f32 v209, v60, v61
	v_add_f32_e32 v190, v190, v191
	v_add_f32_e32 v192, v192, v193
	v_add_f32_e32 v190, v190, v192
	v_mov_b32_e32 v168, v190
	global_store_dwordx4 v[166:167], v[206:209], off
	v_fma_f32 v54, v54, v219, v38
	v_fma_f32 v55, v55, v219, v39
	v_fma_f32 v56, v56, v219, v40
	v_fma_f32 v57, v57, v219, v41
	v_fma_f32 v50, v50, v219, v34
	v_fma_f32 v51, v51, v219, v35
	v_fma_f32 v52, v52, v219, v36
	v_fma_f32 v53, v53, v219, v37
	v_mul_f32_e32 v190, v54, v54
	v_mul_f32_e32 v191, v55, v55
	v_mul_f32_e32 v192, v56, v56
	v_mul_f32_e32 v193, v57, v57
	v_mul_f32_e32 v194, v50, v50
	v_mul_f32_e32 v195, v51, v51
	v_mul_f32_e32 v196, v52, v52
	v_mul_f32_e32 v197, v53, v53
	v_fmaak_f32 v190, v190, v170, 0xc0135761
	v_fmaak_f32 v191, v191, v170, 0xc0135761
	v_fmaak_f32 v192, v192, v170, 0xc0135761
	v_fmaak_f32 v193, v193, v170, 0xc0135761
	v_fmaak_f32 v194, v194, v170, 0xc0135761
	v_fmaak_f32 v195, v195, v170, 0xc0135761
	v_fmaak_f32 v196, v196, v170, 0xc0135761
	v_fmaak_f32 v197, v197, v170, 0xc0135761
	v_mul_f32_e32 v190, v190, v54
	v_mul_f32_e32 v191, v191, v55
	v_mul_f32_e32 v192, v192, v56
	v_mul_f32_e32 v193, v193, v57
	v_mul_f32_e32 v194, v194, v50
	v_mul_f32_e32 v195, v195, v51
	v_mul_f32_e32 v196, v196, v52
	v_mul_f32_e32 v197, v197, v53
	v_exp_f32_e32 v190, v190
	v_exp_f32_e32 v191, v191
	v_exp_f32_e32 v192, v192
	v_exp_f32_e32 v193, v193
	v_exp_f32_e32 v194, v194
	v_exp_f32_e32 v195, v195
	v_exp_f32_e32 v196, v196
	v_exp_f32_e32 v197, v197
	v_add_f32_e32 v190, 1.0, v190
	v_add_f32_e32 v191, 1.0, v191
	v_add_f32_e32 v192, 1.0, v192
	v_add_f32_e32 v193, 1.0, v193
	v_add_f32_e32 v194, 1.0, v194
	v_add_f32_e32 v195, 1.0, v195
	v_add_f32_e32 v196, 1.0, v196
	v_add_f32_e32 v197, 1.0, v197
	v_rcp_f32_e32 v190, v190
	v_rcp_f32_e32 v191, v191
	v_rcp_f32_e32 v192, v192
	v_rcp_f32_e32 v193, v193
	v_rcp_f32_e32 v194, v194
	v_rcp_f32_e32 v195, v195
	v_rcp_f32_e32 v196, v196
	v_rcp_f32_e32 v197, v197
	v_mul_f32_e32 v54, v54, v190
	v_mul_f32_e32 v55, v55, v191
	v_mul_f32_e32 v56, v56, v192
	v_mul_f32_e32 v57, v57, v193
	v_mul_f32_e32 v50, v50, v194
	v_mul_f32_e32 v51, v51, v195
	v_mul_f32_e32 v52, v52, v196
	v_mul_f32_e32 v53, v53, v197
	v_mul_f32_e32 v190, v54, v54
	v_mul_f32_e32 v191, v56, v56
	v_mul_f32_e32 v192, v50, v50
	v_mul_f32_e32 v193, v52, v52
	v_fmac_f32_e32 v190, v55, v55
	v_fmac_f32_e32 v191, v57, v57
	v_fmac_f32_e32 v192, v51, v51
	v_fmac_f32_e32 v193, v53, v53
	v_cvt_pk_bf16_f32 v210, v54, v55
	v_cvt_pk_bf16_f32 v211, v56, v57
	v_cvt_pk_bf16_f32 v212, v50, v51
	v_cvt_pk_bf16_f32 v213, v52, v53
	v_add_f32_e32 v190, v190, v191
	v_add_f32_e32 v192, v192, v193
	v_add_f32_e32 v190, v190, v192
	v_add_f32_e32 v168, v168, v190
	global_store_dwordx4 v[166:167], v[210:213], off offset:256
	s_cmp_lg_u32 s10, 4
	s_cbranch_scc1 .Lwin_noat_l0_5
	ds_bpermute_b32 v171, v224, v168
	v_ashrrev_i32_e32 v173, 31, v169
	v_mov_b32_e32 v172, v169
	s_waitcnt lgkmcnt(0)
	v_add_f32_e32 v168, v168, v171
	ds_bpermute_b32 v171, v225, v168
	v_lshl_add_u64 v[172:173], v[172:173], 2, s[48:49]
	s_waitcnt lgkmcnt(0)
	v_add_f32_e32 v168, v168, v171
	s_mov_b64 s[84:85], exec
	s_and_b64 exec, exec, s[0:1]
	global_atomic_add_f32 v[172:173], v168, off
	s_mov_b64 exec, s[84:85]
.Lwin_noat_l0_5:
	v_fma_f32 v30, v30, v220, v42
	v_fma_f32 v31, v31, v220, v43
	v_fma_f32 v32, v32, v220, v44
	v_fma_f32 v33, v33, v220, v45
	v_fma_f32 v26, v26, v220, v46
	v_fma_f32 v27, v27, v220, v47
	v_fma_f32 v28, v28, v220, v48
	v_fma_f32 v29, v29, v220, v49
	v_mul_f32_e32 v190, v30, v30
	v_mul_f32_e32 v191, v31, v31
	v_mul_f32_e32 v192, v32, v32
	v_mul_f32_e32 v193, v33, v33
	v_mul_f32_e32 v194, v26, v26
	v_mul_f32_e32 v195, v27, v27
	v_mul_f32_e32 v196, v28, v28
	v_mul_f32_e32 v197, v29, v29
	v_fmaak_f32 v190, v190, v170, 0xc0135761
	v_fmaak_f32 v191, v191, v170, 0xc0135761
	v_fmaak_f32 v192, v192, v170, 0xc0135761
	v_fmaak_f32 v193, v193, v170, 0xc0135761
	v_fmaak_f32 v194, v194, v170, 0xc0135761
	v_fmaak_f32 v195, v195, v170, 0xc0135761
	v_fmaak_f32 v196, v196, v170, 0xc0135761
	v_fmaak_f32 v197, v197, v170, 0xc0135761
	v_add_u32_e32 v169, s23, v181
	v_mad_i64_i32 v[228:229], s[8:9], v169, s22, v[226:227]
	v_mul_f32_e32 v190, v190, v30
	v_mul_f32_e32 v191, v191, v31
	v_mul_f32_e32 v192, v192, v32
	v_mul_f32_e32 v193, v193, v33
	v_mul_f32_e32 v194, v194, v26
	v_mul_f32_e32 v195, v195, v27
	v_mul_f32_e32 v196, v196, v28
	v_mul_f32_e32 v197, v197, v29
	v_exp_f32_e32 v190, v190
	v_exp_f32_e32 v191, v191
	v_exp_f32_e32 v192, v192
	v_exp_f32_e32 v193, v193
	v_exp_f32_e32 v194, v194
	v_exp_f32_e32 v195, v195
	v_exp_f32_e32 v196, v196
	v_exp_f32_e32 v197, v197
	v_add_f32_e32 v190, 1.0, v190
	v_add_f32_e32 v191, 1.0, v191
	v_add_f32_e32 v192, 1.0, v192
	v_add_f32_e32 v193, 1.0, v193
	v_add_f32_e32 v194, 1.0, v194
	v_add_f32_e32 v195, 1.0, v195
	v_add_f32_e32 v196, 1.0, v196
	v_add_f32_e32 v197, 1.0, v197
	v_rcp_f32_e32 v190, v190
	v_rcp_f32_e32 v191, v191
	v_rcp_f32_e32 v192, v192
	v_rcp_f32_e32 v193, v193
	v_rcp_f32_e32 v194, v194
	v_rcp_f32_e32 v195, v195
	v_rcp_f32_e32 v196, v196
	v_rcp_f32_e32 v197, v197
	v_mul_f32_e32 v30, v30, v190
	v_mul_f32_e32 v31, v31, v191
	v_mul_f32_e32 v32, v32, v192
	v_mul_f32_e32 v33, v33, v193
	v_mul_f32_e32 v26, v26, v194
	v_mul_f32_e32 v27, v27, v195
	v_mul_f32_e32 v28, v28, v196
	v_mul_f32_e32 v29, v29, v197
	v_mul_f32_e32 v190, v30, v30
	v_mul_f32_e32 v191, v32, v32
	v_mul_f32_e32 v192, v26, v26
	v_mul_f32_e32 v193, v28, v28
	v_fmac_f32_e32 v190, v31, v31
	v_fmac_f32_e32 v191, v33, v33
	v_fmac_f32_e32 v192, v27, v27
	v_fmac_f32_e32 v193, v29, v29
	v_cvt_pk_bf16_f32 v198, v30, v31
	v_cvt_pk_bf16_f32 v199, v32, v33
	v_cvt_pk_bf16_f32 v200, v26, v27
	v_cvt_pk_bf16_f32 v201, v28, v29
	v_add_f32_e32 v190, v190, v191
	v_add_f32_e32 v192, v192, v193
	v_add_f32_e32 v190, v190, v192
	v_mov_b32_e32 v168, v190
	global_store_dwordx4 v[228:229], v[198:201], off
	v_fma_f32 v22, v22, v220, v38
	v_fma_f32 v23, v23, v220, v39
	v_fma_f32 v24, v24, v220, v40
	v_fma_f32 v25, v25, v220, v41
	v_fma_f32 v18, v18, v220, v34
	v_fma_f32 v19, v19, v220, v35
	v_fma_f32 v20, v20, v220, v36
	v_fma_f32 v21, v21, v220, v37
	v_mul_f32_e32 v190, v22, v22
	v_mul_f32_e32 v191, v23, v23
	v_mul_f32_e32 v192, v24, v24
	v_mul_f32_e32 v193, v25, v25
	v_mul_f32_e32 v194, v18, v18
	v_mul_f32_e32 v195, v19, v19
	v_mul_f32_e32 v196, v20, v20
	v_mul_f32_e32 v197, v21, v21
	v_fmaak_f32 v190, v190, v170, 0xc0135761
	v_fmaak_f32 v191, v191, v170, 0xc0135761
	v_fmaak_f32 v192, v192, v170, 0xc0135761
	v_fmaak_f32 v193, v193, v170, 0xc0135761
	v_fmaak_f32 v194, v194, v170, 0xc0135761
	v_fmaak_f32 v195, v195, v170, 0xc0135761
	v_fmaak_f32 v196, v196, v170, 0xc0135761
	v_fmaak_f32 v197, v197, v170, 0xc0135761
	v_mul_f32_e32 v190, v190, v22
	v_mul_f32_e32 v191, v191, v23
	v_mul_f32_e32 v192, v192, v24
	v_mul_f32_e32 v193, v193, v25
	v_mul_f32_e32 v194, v194, v18
	v_mul_f32_e32 v195, v195, v19
	v_mul_f32_e32 v196, v196, v20
	v_mul_f32_e32 v197, v197, v21
	v_exp_f32_e32 v190, v190
	v_exp_f32_e32 v191, v191
	v_exp_f32_e32 v192, v192
	v_exp_f32_e32 v193, v193
	v_exp_f32_e32 v194, v194
	v_exp_f32_e32 v195, v195
	v_exp_f32_e32 v196, v196
	v_exp_f32_e32 v197, v197
	v_add_f32_e32 v190, 1.0, v190
	v_add_f32_e32 v191, 1.0, v191
	v_add_f32_e32 v192, 1.0, v192
	v_add_f32_e32 v193, 1.0, v193
	v_add_f32_e32 v194, 1.0, v194
	v_add_f32_e32 v195, 1.0, v195
	v_add_f32_e32 v196, 1.0, v196
	v_add_f32_e32 v197, 1.0, v197
	v_rcp_f32_e32 v190, v190
	v_rcp_f32_e32 v191, v191
	v_rcp_f32_e32 v192, v192
	v_rcp_f32_e32 v193, v193
	v_rcp_f32_e32 v194, v194
	v_rcp_f32_e32 v195, v195
	v_rcp_f32_e32 v196, v196
	v_rcp_f32_e32 v197, v197
	v_mul_f32_e32 v22, v22, v190
	v_mul_f32_e32 v23, v23, v191
	v_mul_f32_e32 v24, v24, v192
	v_mul_f32_e32 v25, v25, v193
	v_mul_f32_e32 v18, v18, v194
	v_mul_f32_e32 v19, v19, v195
	v_mul_f32_e32 v20, v20, v196
	v_mul_f32_e32 v21, v21, v197
	v_mul_f32_e32 v190, v22, v22
	v_mul_f32_e32 v191, v24, v24
	v_mul_f32_e32 v192, v18, v18
	v_mul_f32_e32 v193, v20, v20
	v_fmac_f32_e32 v190, v23, v23
	v_fmac_f32_e32 v191, v25, v25
	v_fmac_f32_e32 v192, v19, v19
	v_fmac_f32_e32 v193, v21, v21
	v_cvt_pk_bf16_f32 v202, v22, v23
	v_cvt_pk_bf16_f32 v203, v24, v25
	v_cvt_pk_bf16_f32 v204, v18, v19
	v_cvt_pk_bf16_f32 v205, v20, v21
	v_add_f32_e32 v190, v190, v191
	v_add_f32_e32 v192, v192, v193
	v_add_f32_e32 v190, v190, v192
	v_add_f32_e32 v168, v168, v190
	global_store_dwordx4 v[228:229], v[202:205], off offset:256
	s_cmp_lg_u32 s10, 4
	s_cbranch_scc1 .Lwin_noat_l0_6
	ds_bpermute_b32 v171, v224, v168
	v_ashrrev_i32_e32 v173, 31, v169
	v_mov_b32_e32 v172, v169
	s_waitcnt lgkmcnt(0)
	v_add_f32_e32 v168, v168, v171
	ds_bpermute_b32 v171, v225, v168
	v_lshl_add_u64 v[172:173], v[172:173], 2, s[48:49]
	s_waitcnt lgkmcnt(0)
	v_add_f32_e32 v168, v168, v171
	s_mov_b64 s[84:85], exec
	s_and_b64 exec, exec, s[0:1]
	global_atomic_add_f32 v[172:173], v168, off
	s_mov_b64 exec, s[84:85]
.Lwin_noat_l0_6:
	v_fma_f32 v14, v14, v221, v42
	v_fma_f32 v15, v15, v221, v43
	v_fma_f32 v16, v16, v221, v44
	v_fma_f32 v17, v17, v221, v45
	v_fma_f32 v10, v10, v221, v46
	v_fma_f32 v11, v11, v221, v47
	v_fma_f32 v12, v12, v221, v48
	v_fma_f32 v13, v13, v221, v49
	v_mul_f32_e32 v190, v14, v14
	v_mul_f32_e32 v191, v15, v15
	v_mul_f32_e32 v192, v16, v16
	v_mul_f32_e32 v193, v17, v17
	v_mul_f32_e32 v194, v10, v10
	v_mul_f32_e32 v195, v11, v11
	v_mul_f32_e32 v196, v12, v12
	v_mul_f32_e32 v197, v13, v13
	v_fmaak_f32 v190, v190, v170, 0xc0135761
	v_fmaak_f32 v191, v191, v170, 0xc0135761
	v_fmaak_f32 v192, v192, v170, 0xc0135761
	v_fmaak_f32 v193, v193, v170, 0xc0135761
	v_fmaak_f32 v194, v194, v170, 0xc0135761
	v_fmaak_f32 v195, v195, v170, 0xc0135761
	v_fmaak_f32 v196, v196, v170, 0xc0135761
	v_fmaak_f32 v197, v197, v170, 0xc0135761
	v_add_u32_e32 v169, s23, v182
	v_mad_i64_i32 v[166:167], s[8:9], v169, s22, v[226:227]
	v_mul_f32_e32 v190, v190, v14
	v_mul_f32_e32 v191, v191, v15
	v_mul_f32_e32 v192, v192, v16
	v_mul_f32_e32 v193, v193, v17
	v_mul_f32_e32 v194, v194, v10
	v_mul_f32_e32 v195, v195, v11
	v_mul_f32_e32 v196, v196, v12
	v_mul_f32_e32 v197, v197, v13
	v_exp_f32_e32 v190, v190
	v_exp_f32_e32 v191, v191
	v_exp_f32_e32 v192, v192
	v_exp_f32_e32 v193, v193
	v_exp_f32_e32 v194, v194
	v_exp_f32_e32 v195, v195
	v_exp_f32_e32 v196, v196
	v_exp_f32_e32 v197, v197
	v_add_f32_e32 v190, 1.0, v190
	v_add_f32_e32 v191, 1.0, v191
	v_add_f32_e32 v192, 1.0, v192
	v_add_f32_e32 v193, 1.0, v193
	v_add_f32_e32 v194, 1.0, v194
	v_add_f32_e32 v195, 1.0, v195
	v_add_f32_e32 v196, 1.0, v196
	v_add_f32_e32 v197, 1.0, v197
	v_rcp_f32_e32 v190, v190
	v_rcp_f32_e32 v191, v191
	v_rcp_f32_e32 v192, v192
	v_rcp_f32_e32 v193, v193
	v_rcp_f32_e32 v194, v194
	v_rcp_f32_e32 v195, v195
	v_rcp_f32_e32 v196, v196
	v_rcp_f32_e32 v197, v197
	v_mul_f32_e32 v14, v14, v190
	v_mul_f32_e32 v15, v15, v191
	v_mul_f32_e32 v16, v16, v192
	v_mul_f32_e32 v17, v17, v193
	v_mul_f32_e32 v10, v10, v194
	v_mul_f32_e32 v11, v11, v195
	v_mul_f32_e32 v12, v12, v196
	v_mul_f32_e32 v13, v13, v197
	v_mul_f32_e32 v190, v14, v14
	v_mul_f32_e32 v191, v16, v16
	v_mul_f32_e32 v192, v10, v10
	v_mul_f32_e32 v193, v12, v12
	v_fmac_f32_e32 v190, v15, v15
	v_fmac_f32_e32 v191, v17, v17
	v_fmac_f32_e32 v192, v11, v11
	v_fmac_f32_e32 v193, v13, v13
	v_cvt_pk_bf16_f32 v206, v14, v15
	v_cvt_pk_bf16_f32 v207, v16, v17
	v_cvt_pk_bf16_f32 v208, v10, v11
	v_cvt_pk_bf16_f32 v209, v12, v13
	v_add_f32_e32 v190, v190, v191
	v_add_f32_e32 v192, v192, v193
	v_add_f32_e32 v190, v190, v192
	v_mov_b32_e32 v168, v190
	global_store_dwordx4 v[166:167], v[206:209], off
	v_fma_f32 v6, v6, v221, v38
	v_fma_f32 v7, v7, v221, v39
	v_fma_f32 v8, v8, v221, v40
	v_fma_f32 v9, v9, v221, v41
	v_fma_f32 v2, v2, v221, v34
	v_fma_f32 v3, v3, v221, v35
	v_fma_f32 v4, v4, v221, v36
	v_fma_f32 v5, v5, v221, v37
	v_mul_f32_e32 v190, v6, v6
	v_mul_f32_e32 v191, v7, v7
	v_mul_f32_e32 v192, v8, v8
	v_mul_f32_e32 v193, v9, v9
	v_mul_f32_e32 v194, v2, v2
	v_mul_f32_e32 v195, v3, v3
	v_mul_f32_e32 v196, v4, v4
	v_mul_f32_e32 v197, v5, v5
	v_fmaak_f32 v190, v190, v170, 0xc0135761
	v_fmaak_f32 v191, v191, v170, 0xc0135761
	v_fmaak_f32 v192, v192, v170, 0xc0135761
	v_fmaak_f32 v193, v193, v170, 0xc0135761
	v_fmaak_f32 v194, v194, v170, 0xc0135761
	v_fmaak_f32 v195, v195, v170, 0xc0135761
	v_fmaak_f32 v196, v196, v170, 0xc0135761
	v_fmaak_f32 v197, v197, v170, 0xc0135761
	v_mul_f32_e32 v190, v190, v6
	v_mul_f32_e32 v191, v191, v7
	v_mul_f32_e32 v192, v192, v8
	v_mul_f32_e32 v193, v193, v9
	v_mul_f32_e32 v194, v194, v2
	v_mul_f32_e32 v195, v195, v3
	v_mul_f32_e32 v196, v196, v4
	v_mul_f32_e32 v197, v197, v5
	v_exp_f32_e32 v190, v190
	v_exp_f32_e32 v191, v191
	v_exp_f32_e32 v192, v192
	v_exp_f32_e32 v193, v193
	v_exp_f32_e32 v194, v194
	v_exp_f32_e32 v195, v195
	v_exp_f32_e32 v196, v196
	v_exp_f32_e32 v197, v197
	v_add_f32_e32 v190, 1.0, v190
	v_add_f32_e32 v191, 1.0, v191
	v_add_f32_e32 v192, 1.0, v192
	v_add_f32_e32 v193, 1.0, v193
	v_add_f32_e32 v194, 1.0, v194
	v_add_f32_e32 v195, 1.0, v195
	v_add_f32_e32 v196, 1.0, v196
	v_add_f32_e32 v197, 1.0, v197
	v_rcp_f32_e32 v190, v190
	v_rcp_f32_e32 v191, v191
	v_rcp_f32_e32 v192, v192
	v_rcp_f32_e32 v193, v193
	v_rcp_f32_e32 v194, v194
	v_rcp_f32_e32 v195, v195
	v_rcp_f32_e32 v196, v196
	v_rcp_f32_e32 v197, v197
	v_mul_f32_e32 v6, v6, v190
	v_mul_f32_e32 v7, v7, v191
	v_mul_f32_e32 v8, v8, v192
	v_mul_f32_e32 v9, v9, v193
	v_mul_f32_e32 v2, v2, v194
	v_mul_f32_e32 v3, v3, v195
	v_mul_f32_e32 v4, v4, v196
	v_mul_f32_e32 v5, v5, v197
	v_mul_f32_e32 v190, v6, v6
	v_mul_f32_e32 v191, v8, v8
	v_mul_f32_e32 v192, v2, v2
	v_mul_f32_e32 v193, v4, v4
	v_fmac_f32_e32 v190, v7, v7
	v_fmac_f32_e32 v191, v9, v9
	v_fmac_f32_e32 v192, v3, v3
	v_fmac_f32_e32 v193, v5, v5
	v_cvt_pk_bf16_f32 v210, v6, v7
	v_cvt_pk_bf16_f32 v211, v8, v9
	v_cvt_pk_bf16_f32 v212, v2, v3
	v_cvt_pk_bf16_f32 v213, v4, v5
	v_add_f32_e32 v190, v190, v191
	v_add_f32_e32 v192, v192, v193
	v_add_f32_e32 v190, v190, v192
	v_add_f32_e32 v168, v168, v190
	global_store_dwordx4 v[166:167], v[210:213], off offset:256
	s_cmp_lg_u32 s10, 4
	s_cbranch_scc1 .Lwin_noat_l0_7
	ds_bpermute_b32 v171, v224, v168
	v_ashrrev_i32_e32 v173, 31, v169
	v_mov_b32_e32 v172, v169
	s_waitcnt lgkmcnt(0)
	v_add_f32_e32 v168, v168, v171
	ds_bpermute_b32 v171, v225, v168
	v_lshl_add_u64 v[172:173], v[172:173], 2, s[48:49]
	s_waitcnt lgkmcnt(0)
	v_add_f32_e32 v168, v168, v171
	s_mov_b64 s[84:85], exec
	s_and_b64 exec, exec, s[0:1]
	global_atomic_add_f32 v[172:173], v168, off
	s_mov_b64 exec, s[84:85]

.Lwin_plain_l0:
	v_fma_f32 v142, v142, v214, v42
	v_fma_f32 v143, v143, v214, v43
	v_fma_f32 v144, v144, v214, v44
	v_fma_f32 v145, v145, v214, v45
	v_fma_f32 v138, v138, v214, v46
	v_fma_f32 v139, v139, v214, v47
	v_fma_f32 v140, v140, v214, v48
	v_fma_f32 v141, v141, v214, v49
	v_add_u32_e32 v169, s23, v1
	v_mad_i64_i32 v[228:229], s[8:9], v169, s22, v[226:227]
	v_cvt_pk_bf16_f32 v198, v142, v143
	v_cvt_pk_bf16_f32 v199, v144, v145
	v_cvt_pk_bf16_f32 v200, v138, v139
	v_cvt_pk_bf16_f32 v201, v140, v141
	global_store_dwordx4 v[228:229], v[198:201], off
	v_fma_f32 v134, v134, v214, v38
	v_fma_f32 v135, v135, v214, v39
	v_fma_f32 v136, v136, v214, v40
	v_fma_f32 v137, v137, v214, v41
	v_fma_f32 v130, v130, v214, v34
	v_fma_f32 v131, v131, v214, v35
	v_fma_f32 v132, v132, v214, v36
	v_fma_f32 v133, v133, v214, v37
	v_cvt_pk_bf16_f32 v202, v134, v135
	v_cvt_pk_bf16_f32 v203, v136, v137
	v_cvt_pk_bf16_f32 v204, v130, v131
	v_cvt_pk_bf16_f32 v205, v132, v133
	global_store_dwordx4 v[228:229], v[202:205], off offset:256
	v_fma_f32 v126, v126, v215, v42
	v_fma_f32 v127, v127, v215, v43
	v_fma_f32 v128, v128, v215, v44
	v_fma_f32 v129, v129, v215, v45
	v_fma_f32 v122, v122, v215, v46
	v_fma_f32 v123, v123, v215, v47
	v_fma_f32 v124, v124, v215, v48
	v_fma_f32 v125, v125, v215, v49
	v_add_u32_e32 v169, s23, v176
	v_mad_i64_i32 v[166:167], s[8:9], v169, s22, v[226:227]
	v_cvt_pk_bf16_f32 v206, v126, v127
	v_cvt_pk_bf16_f32 v207, v128, v129
	v_cvt_pk_bf16_f32 v208, v122, v123
	v_cvt_pk_bf16_f32 v209, v124, v125
	global_store_dwordx4 v[166:167], v[206:209], off
	v_fma_f32 v118, v118, v215, v38
	v_fma_f32 v119, v119, v215, v39
	v_fma_f32 v120, v120, v215, v40
	v_fma_f32 v121, v121, v215, v41
	v_fma_f32 v114, v114, v215, v34
	v_fma_f32 v115, v115, v215, v35
	v_fma_f32 v116, v116, v215, v36
	v_fma_f32 v117, v117, v215, v37
	v_cvt_pk_bf16_f32 v210, v118, v119
	v_cvt_pk_bf16_f32 v211, v120, v121
	v_cvt_pk_bf16_f32 v212, v114, v115
	v_cvt_pk_bf16_f32 v213, v116, v117
	global_store_dwordx4 v[166:167], v[210:213], off offset:256
	v_fma_f32 v110, v110, v216, v42
	v_fma_f32 v111, v111, v216, v43
	v_fma_f32 v112, v112, v216, v44
	v_fma_f32 v113, v113, v216, v45
	v_fma_f32 v106, v106, v216, v46
	v_fma_f32 v107, v107, v216, v47
	v_fma_f32 v108, v108, v216, v48
	v_fma_f32 v109, v109, v216, v49
	v_add_u32_e32 v169, s23, v177
	v_mad_i64_i32 v[228:229], s[8:9], v169, s22, v[226:227]
	v_cvt_pk_bf16_f32 v198, v110, v111
	v_cvt_pk_bf16_f32 v199, v112, v113
	v_cvt_pk_bf16_f32 v200, v106, v107
	v_cvt_pk_bf16_f32 v201, v108, v109
	global_store_dwordx4 v[228:229], v[198:201], off
	v_fma_f32 v102, v102, v216, v38
	v_fma_f32 v103, v103, v216, v39
	v_fma_f32 v104, v104, v216, v40
	v_fma_f32 v105, v105, v216, v41
	v_fma_f32 v98, v98, v216, v34
	v_fma_f32 v99, v99, v216, v35
	v_fma_f32 v100, v100, v216, v36
	v_fma_f32 v101, v101, v216, v37
	v_cvt_pk_bf16_f32 v202, v102, v103
	v_cvt_pk_bf16_f32 v203, v104, v105
	v_cvt_pk_bf16_f32 v204, v98, v99
	v_cvt_pk_bf16_f32 v205, v100, v101
	global_store_dwordx4 v[228:229], v[202:205], off offset:256
	v_fma_f32 v94, v94, v217, v42
	v_fma_f32 v95, v95, v217, v43
	v_fma_f32 v96, v96, v217, v44
	v_fma_f32 v97, v97, v217, v45
	v_fma_f32 v90, v90, v217, v46
	v_fma_f32 v91, v91, v217, v47
	v_fma_f32 v92, v92, v217, v48
	v_fma_f32 v93, v93, v217, v49
	v_add_u32_e32 v169, s23, v178
	v_mad_i64_i32 v[166:167], s[8:9], v169, s22, v[226:227]
	v_cvt_pk_bf16_f32 v206, v94, v95
	v_cvt_pk_bf16_f32 v207, v96, v97
	v_cvt_pk_bf16_f32 v208, v90, v91
	v_cvt_pk_bf16_f32 v209, v92, v93
	global_store_dwordx4 v[166:167], v[206:209], off
	v_fma_f32 v86, v86, v217, v38
	v_fma_f32 v87, v87, v217, v39
	v_fma_f32 v88, v88, v217, v40
	v_fma_f32 v89, v89, v217, v41
	v_fma_f32 v82, v82, v217, v34
	v_fma_f32 v83, v83, v217, v35
	v_fma_f32 v84, v84, v217, v36
	v_fma_f32 v85, v85, v217, v37
	v_cvt_pk_bf16_f32 v210, v86, v87
	v_cvt_pk_bf16_f32 v211, v88, v89
	v_cvt_pk_bf16_f32 v212, v82, v83
	v_cvt_pk_bf16_f32 v213, v84, v85
	global_store_dwordx4 v[166:167], v[210:213], off offset:256
	v_fma_f32 v78, v78, v218, v42
	v_fma_f32 v79, v79, v218, v43
	v_fma_f32 v80, v80, v218, v44
	v_fma_f32 v81, v81, v218, v45
	v_fma_f32 v74, v74, v218, v46
	v_fma_f32 v75, v75, v218, v47
	v_fma_f32 v76, v76, v218, v48
	v_fma_f32 v77, v77, v218, v49
	v_add_u32_e32 v169, s23, v179
	v_mad_i64_i32 v[228:229], s[8:9], v169, s22, v[226:227]
	v_cvt_pk_bf16_f32 v198, v78, v79
	v_cvt_pk_bf16_f32 v199, v80, v81
	v_cvt_pk_bf16_f32 v200, v74, v75
	v_cvt_pk_bf16_f32 v201, v76, v77
	global_store_dwordx4 v[228:229], v[198:201], off
	v_fma_f32 v70, v70, v218, v38
	v_fma_f32 v71, v71, v218, v39
	v_fma_f32 v72, v72, v218, v40
	v_fma_f32 v73, v73, v218, v41
	v_fma_f32 v66, v66, v218, v34
	v_fma_f32 v67, v67, v218, v35
	v_fma_f32 v68, v68, v218, v36
	v_fma_f32 v69, v69, v218, v37
	v_cvt_pk_bf16_f32 v202, v70, v71
	v_cvt_pk_bf16_f32 v203, v72, v73
	v_cvt_pk_bf16_f32 v204, v66, v67
	v_cvt_pk_bf16_f32 v205, v68, v69
	global_store_dwordx4 v[228:229], v[202:205], off offset:256
	v_fma_f32 v62, v62, v219, v42
	v_fma_f32 v63, v63, v219, v43
	v_fma_f32 v64, v64, v219, v44
	v_fma_f32 v65, v65, v219, v45
	v_fma_f32 v58, v58, v219, v46
	v_fma_f32 v59, v59, v219, v47
	v_fma_f32 v60, v60, v219, v48
	v_fma_f32 v61, v61, v219, v49
	v_add_u32_e32 v169, s23, v180
	v_mad_i64_i32 v[166:167], s[8:9], v169, s22, v[226:227]
	v_cvt_pk_bf16_f32 v206, v62, v63
	v_cvt_pk_bf16_f32 v207, v64, v65
	v_cvt_pk_bf16_f32 v208, v58, v59
	v_cvt_pk_bf16_f32 v209, v60, v61
	global_store_dwordx4 v[166:167], v[206:209], off
	v_fma_f32 v54, v54, v219, v38
	v_fma_f32 v55, v55, v219, v39
	v_fma_f32 v56, v56, v219, v40
	v_fma_f32 v57, v57, v219, v41
	v_fma_f32 v50, v50, v219, v34
	v_fma_f32 v51, v51, v219, v35
	v_fma_f32 v52, v52, v219, v36
	v_fma_f32 v53, v53, v219, v37
	v_cvt_pk_bf16_f32 v210, v54, v55
	v_cvt_pk_bf16_f32 v211, v56, v57
	v_cvt_pk_bf16_f32 v212, v50, v51
	v_cvt_pk_bf16_f32 v213, v52, v53
	global_store_dwordx4 v[166:167], v[210:213], off offset:256
	v_fma_f32 v30, v30, v220, v42
	v_fma_f32 v31, v31, v220, v43
	v_fma_f32 v32, v32, v220, v44
	v_fma_f32 v33, v33, v220, v45
	v_fma_f32 v26, v26, v220, v46
	v_fma_f32 v27, v27, v220, v47
	v_fma_f32 v28, v28, v220, v48
	v_fma_f32 v29, v29, v220, v49
	v_add_u32_e32 v169, s23, v181
	v_mad_i64_i32 v[228:229], s[8:9], v169, s22, v[226:227]
	v_cvt_pk_bf16_f32 v198, v30, v31
	v_cvt_pk_bf16_f32 v199, v32, v33
	v_cvt_pk_bf16_f32 v200, v26, v27
	v_cvt_pk_bf16_f32 v201, v28, v29
	global_store_dwordx4 v[228:229], v[198:201], off
	v_fma_f32 v22, v22, v220, v38
	v_fma_f32 v23, v23, v220, v39
	v_fma_f32 v24, v24, v220, v40
	v_fma_f32 v25, v25, v220, v41
	v_fma_f32 v18, v18, v220, v34
	v_fma_f32 v19, v19, v220, v35
	v_fma_f32 v20, v20, v220, v36
	v_fma_f32 v21, v21, v220, v37
	v_cvt_pk_bf16_f32 v202, v22, v23
	v_cvt_pk_bf16_f32 v203, v24, v25
	v_cvt_pk_bf16_f32 v204, v18, v19
	v_cvt_pk_bf16_f32 v205, v20, v21
	global_store_dwordx4 v[228:229], v[202:205], off offset:256
	v_fma_f32 v14, v14, v221, v42
	v_fma_f32 v15, v15, v221, v43
	v_fma_f32 v16, v16, v221, v44
	v_fma_f32 v17, v17, v221, v45
	v_fma_f32 v10, v10, v221, v46
	v_fma_f32 v11, v11, v221, v47
	v_fma_f32 v12, v12, v221, v48
	v_fma_f32 v13, v13, v221, v49
	v_add_u32_e32 v169, s23, v182
	v_mad_i64_i32 v[166:167], s[8:9], v169, s22, v[226:227]
	v_cvt_pk_bf16_f32 v206, v14, v15
	v_cvt_pk_bf16_f32 v207, v16, v17
	v_cvt_pk_bf16_f32 v208, v10, v11
	v_cvt_pk_bf16_f32 v209, v12, v13
	global_store_dwordx4 v[166:167], v[206:209], off
	v_fma_f32 v6, v6, v221, v38
	v_fma_f32 v7, v7, v221, v39
	v_fma_f32 v8, v8, v221, v40
	v_fma_f32 v9, v9, v221, v41
	v_fma_f32 v2, v2, v221, v34
	v_fma_f32 v3, v3, v221, v35
	v_fma_f32 v4, v4, v221, v36
	v_fma_f32 v5, v5, v221, v37
	v_cvt_pk_bf16_f32 v210, v6, v7
	v_cvt_pk_bf16_f32 v211, v8, v9
	v_cvt_pk_bf16_f32 v212, v2, v3
	v_cvt_pk_bf16_f32 v213, v4, v5
	global_store_dwordx4 v[166:167], v[210:213], off offset:256
.Lwin_end_l0:
.LBB0_296:
	s_andn2_b64 vcc, exec, s[6:7]
	s_mov_b64 s[6:7], -1
	s_cbranch_vccnz .LBB0_189
	s_andn2_b64 vcc, exec, s[36:37]
	s_cbranch_vccnz .LBB0_188
	s_barrier
	s_branch .LBB0_188
